# WO/F2 residual epilogue: xin loads marked nt (streaming, evict-first)
# baseline (speedup 1.0000x reference)
.LBB0_43:
	s_lshl_b32 s3, s42, 8
	v_readlane_b32 s20, v252, 26
	s_add_i32 s20, s3, s20
	s_add_i32 s28, s20, 0xffff8000
	v_readlane_b32 s21, v252, 27
	s_lshr_b32 s28, s28, 13
	s_ashr_i32 s21, s20, 11
	s_add_i32 s28, s28, 16
	s_cmp_lt_i32 s20, 0x8000
	s_cselect_b32 s20, s21, s28
	v_add_u32_e32 v172, s3, v1
	v_lshl_or_b32 v98, s43, 8, v174
	s_mul_hi_i32 s21, s20, 0x6000
	s_mulk_i32 s20, 0x6000
	v_ashrrev_i32_e32 v173, 31, v172
	s_add_u32 s20, s45, s20
	v_ashrrev_i32_e32 v99, 31, v98
	v_lshlrev_b64 v[154:155], 12, v[172:173]
	s_addc_u32 s21, s82, s21
	v_lshlrev_b64 v[170:171], 2, v[98:99]
	v_lshl_add_u64 v[154:155], s[40:41], 0, v[154:155]
	v_lshl_add_u64 v[98:99], s[20:21], 0, v[170:171]
	v_lshl_add_u64 v[154:155], v[154:155], 0, v[170:171]
	global_load_dwordx4 v[130:133], v[98:99], off
	global_load_dwordx4 v[122:125], v[98:99], off offset:64
	global_load_dwordx4 v[114:117], v[98:99], off offset:512
	s_nop 0
	global_load_dwordx4 v[98:101], v[98:99], off offset:576
	s_mov_b32 s3, 0x80000
	v_lshl_add_u32 v248, v172, 12, v170
	s_add_u32 s20, s40, 0x0
	s_addc_u32 s21, s41, 0
	global_load_dwordx4 v[176:179], v248, s[20:21] nt
	global_load_dwordx4 v[180:183], v248, s[20:21] offset:64 nt
	global_load_dwordx4 v[184:187], v248, s[20:21] offset:512 nt
	global_load_dwordx4 v[188:191], v248, s[20:21] offset:576 nt
	s_add_u32 s20, s40, 0x10000
	s_addc_u32 s21, s41, 0
	global_load_dwordx4 v[192:195], v248, s[20:21] nt
	global_load_dwordx4 v[196:199], v248, s[20:21] offset:64 nt
	global_load_dwordx4 v[208:211], v248, s[20:21] offset:512 nt
	global_load_dwordx4 v[212:215], v248, s[20:21] offset:576 nt
	s_add_u32 s20, s40, 0x20000
	s_addc_u32 s21, s41, 0
	global_load_dwordx4 v[216:219], v248, s[20:21] nt
	global_load_dwordx4 v[220:223], v248, s[20:21] offset:64 nt
	global_load_dwordx4 v[224:227], v248, s[20:21] offset:512 nt
	global_load_dwordx4 v[228:231], v248, s[20:21] offset:576 nt
	s_add_u32 s20, s40, 0x30000
	s_addc_u32 s21, s41, 0
	global_load_dwordx4 v[232:235], v248, s[20:21] nt
	global_load_dwordx4 v[236:239], v248, s[20:21] offset:64 nt
	global_load_dwordx4 v[240:243], v248, s[20:21] offset:512 nt
	global_load_dwordx4 v[244:247], v248, s[20:21] offset:576 nt
	s_waitcnt vmcnt(12)
	v_pk_fma_f32 v[144:145], v[144:145], v[132:133], v[178:179]
	v_pk_fma_f32 v[142:143], v[142:143], v[130:131], v[176:177]
	v_pk_fma_f32 v[140:141], v[140:141], v[124:125], v[182:183]
	v_pk_fma_f32 v[138:139], v[138:139], v[122:123], v[180:181]
	v_pk_fma_f32 v[136:137], v[136:137], v[116:117], v[186:187]
	v_pk_fma_f32 v[134:135], v[134:135], v[114:115], v[184:185]
	v_pk_fma_f32 v[128:129], v[128:129], v[100:101], v[190:191]
	v_pk_fma_f32 v[126:127], v[126:127], v[98:99], v[188:189]
	s_add_u32 s48, s40, 0x0
	s_addc_u32 s49, s41, 0
	global_store_dwordx4 v248, v[142:145], s[48:49]
	global_store_dwordx4 v248, v[138:141], s[48:49] offset:64
	global_store_dwordx4 v248, v[134:137], s[48:49] offset:512
	global_store_dwordx4 v248, v[126:129], s[48:49] offset:576
	s_add_u32 s20, s40, 0x80000
	s_addc_u32 s21, s41, 0
	global_load_dwordx4 v[176:179], v248, s[20:21] nt
	global_load_dwordx4 v[180:183], v248, s[20:21] offset:64 nt
	global_load_dwordx4 v[184:187], v248, s[20:21] offset:512 nt
	global_load_dwordx4 v[188:191], v248, s[20:21] offset:576 nt
	s_waitcnt vmcnt(16)
	v_pk_fma_f32 v[120:121], v[120:121], v[132:133], v[194:195]
	v_pk_fma_f32 v[118:119], v[118:119], v[130:131], v[192:193]
	v_pk_fma_f32 v[112:113], v[112:113], v[124:125], v[198:199]
	v_pk_fma_f32 v[110:111], v[110:111], v[122:123], v[196:197]
	v_pk_fma_f32 v[108:109], v[108:109], v[116:117], v[210:211]
	v_pk_fma_f32 v[106:107], v[106:107], v[114:115], v[208:209]
	v_pk_fma_f32 v[104:105], v[104:105], v[100:101], v[214:215]
	v_pk_fma_f32 v[102:103], v[102:103], v[98:99], v[212:213]
	s_add_u32 s48, s40, 0x10000
	s_addc_u32 s49, s41, 0
	global_store_dwordx4 v248, v[118:121], s[48:49]
	global_store_dwordx4 v248, v[110:113], s[48:49] offset:64
	global_store_dwordx4 v248, v[106:109], s[48:49] offset:512
	global_store_dwordx4 v248, v[102:105], s[48:49] offset:576
	s_add_u32 s20, s40, 0x90000
	s_addc_u32 s21, s41, 0
	global_load_dwordx4 v[192:195], v248, s[20:21] nt
	global_load_dwordx4 v[196:199], v248, s[20:21] offset:64 nt
	global_load_dwordx4 v[208:211], v248, s[20:21] offset:512 nt
	global_load_dwordx4 v[212:215], v248, s[20:21] offset:576 nt
	s_waitcnt vmcnt(20)
	v_pk_fma_f32 v[96:97], v[96:97], v[132:133], v[218:219]
	v_pk_fma_f32 v[94:95], v[94:95], v[130:131], v[216:217]
	v_pk_fma_f32 v[92:93], v[92:93], v[124:125], v[222:223]
	v_pk_fma_f32 v[90:91], v[90:91], v[122:123], v[220:221]
	v_pk_fma_f32 v[88:89], v[88:89], v[116:117], v[226:227]
	v_pk_fma_f32 v[86:87], v[86:87], v[114:115], v[224:225]
	v_pk_fma_f32 v[84:85], v[84:85], v[100:101], v[230:231]
	v_pk_fma_f32 v[82:83], v[82:83], v[98:99], v[228:229]
	s_add_u32 s48, s40, 0x20000
	s_addc_u32 s49, s41, 0
	global_store_dwordx4 v248, v[94:97], s[48:49]
	global_store_dwordx4 v248, v[90:93], s[48:49] offset:64
	global_store_dwordx4 v248, v[86:89], s[48:49] offset:512
	global_store_dwordx4 v248, v[82:85], s[48:49] offset:576
	s_add_u32 s20, s40, 0xa0000
	s_addc_u32 s21, s41, 0
	global_load_dwordx4 v[216:219], v248, s[20:21] nt
	global_load_dwordx4 v[220:223], v248, s[20:21] offset:64 nt
	global_load_dwordx4 v[224:227], v248, s[20:21] offset:512 nt
	global_load_dwordx4 v[228:231], v248, s[20:21] offset:576 nt
	s_waitcnt vmcnt(24)
	v_pk_fma_f32 v[80:81], v[80:81], v[132:133], v[234:235]
	v_pk_fma_f32 v[78:79], v[78:79], v[130:131], v[232:233]
	v_pk_fma_f32 v[76:77], v[76:77], v[124:125], v[238:239]
	v_pk_fma_f32 v[74:75], v[74:75], v[122:123], v[236:237]
	v_pk_fma_f32 v[72:73], v[72:73], v[116:117], v[242:243]
	v_pk_fma_f32 v[70:71], v[70:71], v[114:115], v[240:241]
	v_pk_fma_f32 v[68:69], v[68:69], v[100:101], v[246:247]
	v_pk_fma_f32 v[66:67], v[66:67], v[98:99], v[244:245]
	s_add_u32 s48, s40, 0x30000
	s_addc_u32 s49, s41, 0
	global_store_dwordx4 v248, v[78:81], s[48:49]
	global_store_dwordx4 v248, v[74:77], s[48:49] offset:64
	global_store_dwordx4 v248, v[70:73], s[48:49] offset:512
	global_store_dwordx4 v248, v[66:69], s[48:49] offset:576
	s_add_u32 s20, s40, 0xb0000
	s_addc_u32 s21, s41, 0
	global_load_dwordx4 v[232:235], v248, s[20:21] nt
	global_load_dwordx4 v[236:239], v248, s[20:21] offset:64 nt
	global_load_dwordx4 v[240:243], v248, s[20:21] offset:512 nt
	global_load_dwordx4 v[244:247], v248, s[20:21] offset:576 nt
	s_waitcnt vmcnt(24)
	v_pk_fma_f32 v[64:65], v[64:65], v[132:133], v[178:179]
	v_pk_fma_f32 v[62:63], v[62:63], v[130:131], v[176:177]
	v_pk_fma_f32 v[60:61], v[60:61], v[124:125], v[182:183]
	v_pk_fma_f32 v[58:59], v[58:59], v[122:123], v[180:181]
	v_pk_fma_f32 v[56:57], v[56:57], v[116:117], v[186:187]
	v_pk_fma_f32 v[54:55], v[54:55], v[114:115], v[184:185]
	v_pk_fma_f32 v[52:53], v[52:53], v[100:101], v[190:191]
	v_pk_fma_f32 v[50:51], v[50:51], v[98:99], v[188:189]
	s_add_u32 s48, s40, 0x80000
	s_addc_u32 s49, s41, 0
	global_store_dwordx4 v248, v[62:65], s[48:49]
	global_store_dwordx4 v248, v[58:61], s[48:49] offset:64
	global_store_dwordx4 v248, v[54:57], s[48:49] offset:512
	global_store_dwordx4 v248, v[50:53], s[48:49] offset:576
	s_waitcnt vmcnt(20)
	v_pk_fma_f32 v[48:49], v[48:49], v[132:133], v[194:195]
	v_pk_fma_f32 v[46:47], v[46:47], v[130:131], v[192:193]
	v_pk_fma_f32 v[44:45], v[44:45], v[124:125], v[198:199]
	v_pk_fma_f32 v[42:43], v[42:43], v[122:123], v[196:197]
	v_pk_fma_f32 v[40:41], v[40:41], v[116:117], v[210:211]
	v_pk_fma_f32 v[38:39], v[38:39], v[114:115], v[208:209]
	v_pk_fma_f32 v[36:37], v[36:37], v[100:101], v[214:215]
	v_pk_fma_f32 v[34:35], v[34:35], v[98:99], v[212:213]
	s_add_u32 s48, s40, 0x90000
	s_addc_u32 s49, s41, 0
	global_store_dwordx4 v248, v[46:49], s[48:49]
	global_store_dwordx4 v248, v[42:45], s[48:49] offset:64
	global_store_dwordx4 v248, v[38:41], s[48:49] offset:512
	global_store_dwordx4 v248, v[34:37], s[48:49] offset:576
	s_waitcnt vmcnt(16)
	v_pk_fma_f32 v[32:33], v[32:33], v[132:133], v[218:219]
	v_pk_fma_f32 v[30:31], v[30:31], v[130:131], v[216:217]
	v_pk_fma_f32 v[28:29], v[28:29], v[124:125], v[222:223]
	v_pk_fma_f32 v[26:27], v[26:27], v[122:123], v[220:221]
	v_pk_fma_f32 v[24:25], v[24:25], v[116:117], v[226:227]
	v_pk_fma_f32 v[22:23], v[22:23], v[114:115], v[224:225]
	v_pk_fma_f32 v[20:21], v[20:21], v[100:101], v[230:231]
	v_pk_fma_f32 v[18:19], v[18:19], v[98:99], v[228:229]
	s_add_u32 s48, s40, 0xa0000
	s_addc_u32 s49, s41, 0
	global_store_dwordx4 v248, v[30:33], s[48:49]
	global_store_dwordx4 v248, v[26:29], s[48:49] offset:64
	global_store_dwordx4 v248, v[22:25], s[48:49] offset:512
	global_store_dwordx4 v248, v[18:21], s[48:49] offset:576
	s_waitcnt vmcnt(12)
	v_pk_fma_f32 v[16:17], v[16:17], v[132:133], v[234:235]
	v_pk_fma_f32 v[14:15], v[14:15], v[130:131], v[232:233]
	v_pk_fma_f32 v[12:13], v[12:13], v[124:125], v[238:239]
	v_pk_fma_f32 v[10:11], v[10:11], v[122:123], v[236:237]
	v_pk_fma_f32 v[8:9], v[8:9], v[116:117], v[242:243]
	v_pk_fma_f32 v[6:7], v[6:7], v[114:115], v[240:241]
	v_pk_fma_f32 v[4:5], v[4:5], v[100:101], v[246:247]
	v_pk_fma_f32 v[2:3], v[2:3], v[98:99], v[244:245]
	s_add_u32 s48, s40, 0xb0000
	s_addc_u32 s49, s41, 0
	global_store_dwordx4 v248, v[14:17], s[48:49]
	global_store_dwordx4 v248, v[10:13], s[48:49] offset:64
	global_store_dwordx4 v248, v[6:9], s[48:49] offset:512
	global_store_dwordx4 v248, v[2:5], s[48:49] offset:576
	s_mov_b64 s[20:21], -1
	s_and_b64 vcc, exec, s[36:37]
	s_cbranch_vccnz .LBB0_27
	v_readlane_b32 s20, v252, 38
	v_readlane_b32 s21, v252, 39
	s_andn2_b64 vcc, exec, s[20:21]
	s_cbranch_vccnz .LBB0_26
	s_barrier
	s_branch .LBB0_26

.LBB0_105:
	s_lshl_b32 s2, s2, 8
	v_readlane_b32 s20, v252, 26
	v_readlane_b32 s21, v252, 27
	s_add_i32 s13, s2, s20
	s_add_i32 s21, s13, 0xffff8000
	s_lshr_b32 s21, s21, 13
	s_ashr_i32 s20, s13, 11
	s_add_i32 s21, s21, 16
	s_cmp_lt_i32 s13, 0x8000
	v_add_u32_e32 v172, s2, v1
	v_lshl_or_b32 v170, s99, 8, v174
	s_cselect_b32 s13, s20, s21
	v_ashrrev_i32_e32 v173, 31, v172
	s_mul_hi_i32 s21, s13, 0x6000
	s_mulk_i32 s13, 0x6000
	v_ashrrev_i32_e32 v171, 31, v170
	v_lshlrev_b64 v[154:155], 10, v[172:173]
	s_add_u32 s20, s45, s13
	v_lshl_add_u64 v[154:155], v[154:155], 0, v[170:171]
	s_addc_u32 s21, s82, s21
	v_lshlrev_b64 v[154:155], 2, v[154:155]
	v_lshl_add_u64 v[130:131], v[170:171], 2, s[20:21]
	v_lshl_add_u64 v[180:181], s[30:31], 0, v[154:155]
	global_load_dwordx4 v[142:145], v[130:131], off
	global_load_dwordx4 v[138:141], v[130:131], off offset:64
	global_load_dwordx4 v[134:137], v[130:131], off offset:512
	s_nop 0
	global_load_dwordx4 v[130:133], v[130:131], off offset:576
	s_add_u32 s20, s30, 0x0
	s_addc_u32 s21, s31, 0
	global_load_dwordx4 v[176:179], v154, s[20:21] nt
	global_load_dwordx4 v[180:183], v154, s[20:21] offset:64 nt
	global_load_dwordx4 v[184:187], v154, s[20:21] offset:512 nt
	global_load_dwordx4 v[188:191], v154, s[20:21] offset:576 nt
	s_add_u32 s20, s30, 0x10000
	s_addc_u32 s21, s31, 0
	global_load_dwordx4 v[192:195], v154, s[20:21] nt
	global_load_dwordx4 v[196:199], v154, s[20:21] offset:64 nt
	global_load_dwordx4 v[208:211], v154, s[20:21] offset:512 nt
	global_load_dwordx4 v[212:215], v154, s[20:21] offset:576 nt
	s_add_u32 s20, s30, 0x20000
	s_addc_u32 s21, s31, 0
	global_load_dwordx4 v[216:219], v154, s[20:21] nt
	global_load_dwordx4 v[220:223], v154, s[20:21] offset:64 nt
	global_load_dwordx4 v[224:227], v154, s[20:21] offset:512 nt
	global_load_dwordx4 v[228:231], v154, s[20:21] offset:576 nt
	s_add_u32 s20, s30, 0x30000
	s_addc_u32 s21, s31, 0
	global_load_dwordx4 v[232:235], v154, s[20:21] nt
	global_load_dwordx4 v[236:239], v154, s[20:21] offset:64 nt
	global_load_dwordx4 v[240:243], v154, s[20:21] offset:512 nt
	global_load_dwordx4 v[244:247], v154, s[20:21] offset:576 nt
	s_waitcnt vmcnt(12)
	v_pk_fma_f32 v[128:129], v[128:129], v[144:145], v[178:179]
	v_pk_fma_f32 v[126:127], v[126:127], v[142:143], v[176:177]
	v_pk_fma_f32 v[124:125], v[124:125], v[140:141], v[182:183]
	v_pk_fma_f32 v[122:123], v[122:123], v[138:139], v[180:181]
	v_pk_fma_f32 v[120:121], v[120:121], v[136:137], v[186:187]
	v_pk_fma_f32 v[118:119], v[118:119], v[134:135], v[184:185]
	v_pk_fma_f32 v[116:117], v[116:117], v[132:133], v[190:191]
	v_pk_fma_f32 v[114:115], v[114:115], v[130:131], v[188:189]
	s_add_u32 s48, s40, 0x0
	s_addc_u32 s49, s41, 0
	global_store_dwordx4 v154, v[126:129], s[48:49]
	global_store_dwordx4 v154, v[122:125], s[48:49] offset:64
	global_store_dwordx4 v154, v[118:121], s[48:49] offset:512
	global_store_dwordx4 v154, v[114:117], s[48:49] offset:576
	s_add_u32 s20, s30, 0x80000
	s_addc_u32 s21, s31, 0
	global_load_dwordx4 v[176:179], v154, s[20:21] nt
	global_load_dwordx4 v[180:183], v154, s[20:21] offset:64 nt
	global_load_dwordx4 v[184:187], v154, s[20:21] offset:512 nt
	global_load_dwordx4 v[188:191], v154, s[20:21] offset:576 nt
	s_waitcnt vmcnt(16)
	v_pk_fma_f32 v[112:113], v[112:113], v[144:145], v[194:195]
	v_pk_fma_f32 v[110:111], v[110:111], v[142:143], v[192:193]
	v_pk_fma_f32 v[108:109], v[108:109], v[140:141], v[198:199]
	v_pk_fma_f32 v[106:107], v[106:107], v[138:139], v[196:197]
	v_pk_fma_f32 v[104:105], v[104:105], v[136:137], v[210:211]
	v_pk_fma_f32 v[102:103], v[102:103], v[134:135], v[208:209]
	v_pk_fma_f32 v[100:101], v[100:101], v[132:133], v[214:215]
	v_pk_fma_f32 v[98:99], v[98:99], v[130:131], v[212:213]
	s_add_u32 s48, s40, 0x10000
	s_addc_u32 s49, s41, 0
	global_store_dwordx4 v154, v[110:113], s[48:49]
	global_store_dwordx4 v154, v[106:109], s[48:49] offset:64
	global_store_dwordx4 v154, v[102:105], s[48:49] offset:512
	global_store_dwordx4 v154, v[98:101], s[48:49] offset:576
	s_add_u32 s20, s30, 0x90000
	s_addc_u32 s21, s31, 0
	global_load_dwordx4 v[192:195], v154, s[20:21] nt
	global_load_dwordx4 v[196:199], v154, s[20:21] offset:64 nt
	global_load_dwordx4 v[208:211], v154, s[20:21] offset:512 nt
	global_load_dwordx4 v[212:215], v154, s[20:21] offset:576 nt
	s_waitcnt vmcnt(20)
	v_pk_fma_f32 v[96:97], v[96:97], v[144:145], v[218:219]
	v_pk_fma_f32 v[94:95], v[94:95], v[142:143], v[216:217]
	v_pk_fma_f32 v[92:93], v[92:93], v[140:141], v[222:223]
	v_pk_fma_f32 v[90:91], v[90:91], v[138:139], v[220:221]
	v_pk_fma_f32 v[88:89], v[88:89], v[136:137], v[226:227]
	v_pk_fma_f32 v[86:87], v[86:87], v[134:135], v[224:225]
	v_pk_fma_f32 v[84:85], v[84:85], v[132:133], v[230:231]
	v_pk_fma_f32 v[82:83], v[82:83], v[130:131], v[228:229]
	s_add_u32 s48, s40, 0x20000
	s_addc_u32 s49, s41, 0
	global_store_dwordx4 v154, v[94:97], s[48:49]
	global_store_dwordx4 v154, v[90:93], s[48:49] offset:64
	global_store_dwordx4 v154, v[86:89], s[48:49] offset:512
	global_store_dwordx4 v154, v[82:85], s[48:49] offset:576
	s_add_u32 s20, s30, 0xa0000
	s_addc_u32 s21, s31, 0
	global_load_dwordx4 v[216:219], v154, s[20:21] nt
	global_load_dwordx4 v[220:223], v154, s[20:21] offset:64 nt
	global_load_dwordx4 v[224:227], v154, s[20:21] offset:512 nt
	global_load_dwordx4 v[228:231], v154, s[20:21] offset:576 nt
	s_waitcnt vmcnt(24)
	v_pk_fma_f32 v[80:81], v[80:81], v[144:145], v[234:235]
	v_pk_fma_f32 v[78:79], v[78:79], v[142:143], v[232:233]
	v_pk_fma_f32 v[76:77], v[76:77], v[140:141], v[238:239]
	v_pk_fma_f32 v[74:75], v[74:75], v[138:139], v[236:237]
	v_pk_fma_f32 v[72:73], v[72:73], v[136:137], v[242:243]
	v_pk_fma_f32 v[70:71], v[70:71], v[134:135], v[240:241]
	v_pk_fma_f32 v[68:69], v[68:69], v[132:133], v[246:247]
	v_pk_fma_f32 v[66:67], v[66:67], v[130:131], v[244:245]
	s_add_u32 s48, s40, 0x30000
	s_addc_u32 s49, s41, 0
	global_store_dwordx4 v154, v[78:81], s[48:49]
	global_store_dwordx4 v154, v[74:77], s[48:49] offset:64
	global_store_dwordx4 v154, v[70:73], s[48:49] offset:512
	global_store_dwordx4 v154, v[66:69], s[48:49] offset:576
	s_add_u32 s20, s30, 0xb0000
	s_addc_u32 s21, s31, 0
	global_load_dwordx4 v[232:235], v154, s[20:21] nt
	global_load_dwordx4 v[236:239], v154, s[20:21] offset:64 nt
	global_load_dwordx4 v[240:243], v154, s[20:21] offset:512 nt
	global_load_dwordx4 v[244:247], v154, s[20:21] offset:576 nt
	s_waitcnt vmcnt(24)
	v_pk_fma_f32 v[64:65], v[64:65], v[144:145], v[178:179]
	v_pk_fma_f32 v[62:63], v[62:63], v[142:143], v[176:177]
	v_pk_fma_f32 v[60:61], v[60:61], v[140:141], v[182:183]
	v_pk_fma_f32 v[58:59], v[58:59], v[138:139], v[180:181]
	v_pk_fma_f32 v[56:57], v[56:57], v[136:137], v[186:187]
	v_pk_fma_f32 v[54:55], v[54:55], v[134:135], v[184:185]
	v_pk_fma_f32 v[52:53], v[52:53], v[132:133], v[190:191]
	v_pk_fma_f32 v[50:51], v[50:51], v[130:131], v[188:189]
	s_add_u32 s48, s40, 0x80000
	s_addc_u32 s49, s41, 0
	global_store_dwordx4 v154, v[62:65], s[48:49]
	global_store_dwordx4 v154, v[58:61], s[48:49] offset:64
	global_store_dwordx4 v154, v[54:57], s[48:49] offset:512
	global_store_dwordx4 v154, v[50:53], s[48:49] offset:576
	s_waitcnt vmcnt(20)
	v_pk_fma_f32 v[48:49], v[48:49], v[144:145], v[194:195]
	v_pk_fma_f32 v[46:47], v[46:47], v[142:143], v[192:193]
	v_pk_fma_f32 v[44:45], v[44:45], v[140:141], v[198:199]
	v_pk_fma_f32 v[42:43], v[42:43], v[138:139], v[196:197]
	v_pk_fma_f32 v[40:41], v[40:41], v[136:137], v[210:211]
	v_pk_fma_f32 v[38:39], v[38:39], v[134:135], v[208:209]
	v_pk_fma_f32 v[36:37], v[36:37], v[132:133], v[214:215]
	v_pk_fma_f32 v[34:35], v[34:35], v[130:131], v[212:213]
	s_add_u32 s48, s40, 0x90000
	s_addc_u32 s49, s41, 0
	global_store_dwordx4 v154, v[46:49], s[48:49]
	global_store_dwordx4 v154, v[42:45], s[48:49] offset:64
	global_store_dwordx4 v154, v[38:41], s[48:49] offset:512
	global_store_dwordx4 v154, v[34:37], s[48:49] offset:576
	s_waitcnt vmcnt(16)
	v_pk_fma_f32 v[32:33], v[32:33], v[144:145], v[218:219]
	v_pk_fma_f32 v[30:31], v[30:31], v[142:143], v[216:217]
	v_pk_fma_f32 v[28:29], v[28:29], v[140:141], v[222:223]
	v_pk_fma_f32 v[26:27], v[26:27], v[138:139], v[220:221]
	v_pk_fma_f32 v[24:25], v[24:25], v[136:137], v[226:227]
	v_pk_fma_f32 v[22:23], v[22:23], v[134:135], v[224:225]
	v_pk_fma_f32 v[20:21], v[20:21], v[132:133], v[230:231]
	v_pk_fma_f32 v[18:19], v[18:19], v[130:131], v[228:229]
	s_add_u32 s48, s40, 0xa0000
	s_addc_u32 s49, s41, 0
	global_store_dwordx4 v154, v[30:33], s[48:49]
	global_store_dwordx4 v154, v[26:29], s[48:49] offset:64
	global_store_dwordx4 v154, v[22:25], s[48:49] offset:512
	global_store_dwordx4 v154, v[18:21], s[48:49] offset:576
	s_waitcnt vmcnt(12)
	v_pk_fma_f32 v[16:17], v[16:17], v[144:145], v[234:235]
	v_pk_fma_f32 v[14:15], v[14:15], v[142:143], v[232:233]
	v_pk_fma_f32 v[12:13], v[12:13], v[140:141], v[238:239]
	v_pk_fma_f32 v[10:11], v[10:11], v[138:139], v[236:237]
	v_pk_fma_f32 v[8:9], v[8:9], v[136:137], v[242:243]
	v_pk_fma_f32 v[6:7], v[6:7], v[134:135], v[240:241]
	v_pk_fma_f32 v[4:5], v[4:5], v[132:133], v[246:247]
	v_pk_fma_f32 v[2:3], v[2:3], v[130:131], v[244:245]
	s_add_u32 s48, s40, 0xb0000
	s_addc_u32 s49, s41, 0
	global_store_dwordx4 v154, v[14:17], s[48:49]
	global_store_dwordx4 v154, v[10:13], s[48:49] offset:64
	global_store_dwordx4 v154, v[6:9], s[48:49] offset:512
	global_store_dwordx4 v154, v[2:5], s[48:49] offset:576
	s_mov_b64 s[20:21], -1
	s_and_b64 vcc, exec, s[36:37]
	s_cbranch_vccnz .LBB0_89
	v_readlane_b32 s20, v252, 38
	v_readlane_b32 s21, v252, 39
	s_andn2_b64 vcc, exec, s[20:21]
	s_cbranch_vccnz .LBB0_88
	s_barrier
	s_branch .LBB0_88
